# v18: v17 + hand-scheduled layer-A input-projection [u|z] epilogue (gelu/silu chains interleaved, no dependent-op nops, saddr stores)
# speedup vs baseline: 1.0041x; 1.0006x over previous
.LBB0_469:
	v_lshlrev_b32_e32 v144, 2, v142
	global_load_dword v200, v144, s[16:17]
	global_load_dword v202, v144, s[16:17] offset:64
	global_load_dword v204, v144, s[16:17] offset:128
	global_load_dword v206, v144, s[16:17] offset:192
	global_load_dword v208, v144, s[16:17] offset:512
	global_load_dword v210, v144, s[16:17] offset:576
	global_load_dword v212, v144, s[16:17] offset:640
	global_load_dword v214, v144, s[16:17] offset:704
	s_mov_b32 s0, 0xbb7be14b
	s_mov_b32 s2, 0x3bcff2a2
	s_mov_b32 s28, 0xbc40d0ac
	s_mov_b32 s30, 0x3cb76c34
	s_mov_b32 s48, 0xbd17b858
	s_mov_b32 s50, 0x3d6537d1
	s_mov_b32 s52, 0xbdacab04
	s_mov_b32 s54, 0x3e342bfa
	v_mov_b32_e32 v198, s0
	v_lshl_or_b32 v146, s47, 7, v176
	v_lshlrev_b32_e32 v145, 12, v142
	v_lshl_add_u32 v182, v146, 1, v145
	v_add_u32_e32 v183, 0x10000, v182
	v_add_u32_e32 v184, 0x20000, v182
	v_add_u32_e32 v185, 0x30000, v182
	v_add_u32_e32 v186, 0x80000, v182
	v_add_u32_e32 v187, 0x90000, v182
	v_add_u32_e32 v188, 0xa0000, v182
	v_add_u32_e32 v189, 0xb0000, v182
	s_waitcnt vmcnt(0)
	v_pk_mul_f32 v[128:129], v[128:129], v[200:201] op_sel_hi:[1,0]
	v_pk_mul_f32 v[130:131], v[130:131], v[200:201] op_sel_hi:[1,0]
	v_pk_mul_f32 v[120:121], v[120:121], v[200:201] op_sel_hi:[1,0]
	v_pk_mul_f32 v[122:123], v[122:123], v[200:201] op_sel_hi:[1,0]
	v_pk_mul_f32 v[124:125], v[124:125], v[200:201] op_sel_hi:[1,0]
	v_pk_mul_f32 v[126:127], v[126:127], v[200:201] op_sel_hi:[1,0]
	v_pk_mul_f32 v[116:117], v[116:117], v[200:201] op_sel_hi:[1,0]
	v_pk_mul_f32 v[118:119], v[118:119], v[200:201] op_sel_hi:[1,0]
	v_med3_f32 v158, v128, -4.0, 4.0
	v_med3_f32 v164, v130, -4.0, 4.0
	v_mul_f32_e32 v170, 0xbfb8aa3b, v124
	v_med3_f32 v159, v129, -4.0, 4.0
	v_med3_f32 v165, v131, -4.0, 4.0
	v_mul_f32_e32 v171, 0xbfb8aa3b, v125
	v_pk_mul_f32 v[160:161], v[158:159], v[158:159]
	v_pk_mul_f32 v[166:167], v[164:165], v[164:165]
	v_mul_f32_e32 v172, 0xbfb8aa3b, v126
	v_pk_fma_f32 v[160:161], v[160:161], s[72:73], -1.0 op_sel_hi:[1,0,0]
	v_pk_fma_f32 v[166:167], v[166:167], s[72:73], -1.0 op_sel_hi:[1,0,0]
	v_mul_f32_e32 v173, 0xbfb8aa3b, v127
	v_pk_fma_f32 v[162:163], v[160:161], s[74:75], v[198:199] op_sel_hi:[1,0,0]
	v_pk_fma_f32 v[168:169], v[166:167], s[74:75], v[198:199] op_sel_hi:[1,0,0]
	v_exp_f32_e32 v170, v170
	v_pk_fma_f32 v[162:163], v[160:161], v[162:163], s[2:3] op_sel_hi:[1,1,0]
	v_pk_fma_f32 v[168:169], v[166:167], v[168:169], s[2:3] op_sel_hi:[1,1,0]
	v_exp_f32_e32 v171, v171
	v_pk_fma_f32 v[162:163], v[160:161], v[162:163], s[28:29] op_sel_hi:[1,1,0]
	v_pk_fma_f32 v[168:169], v[166:167], v[168:169], s[28:29] op_sel_hi:[1,1,0]
	v_exp_f32_e32 v172, v172
	v_pk_fma_f32 v[162:163], v[160:161], v[162:163], s[30:31] op_sel_hi:[1,1,0]
	v_pk_fma_f32 v[168:169], v[166:167], v[168:169], s[30:31] op_sel_hi:[1,1,0]
	v_exp_f32_e32 v173, v173
	v_pk_fma_f32 v[162:163], v[160:161], v[162:163], s[48:49] op_sel_hi:[1,1,0]
	v_pk_fma_f32 v[168:169], v[166:167], v[168:169], s[48:49] op_sel_hi:[1,1,0]
	v_add_f32_e32 v170, 1.0, v170
	v_pk_fma_f32 v[162:163], v[160:161], v[162:163], s[50:51] op_sel_hi:[1,1,0]
	v_pk_fma_f32 v[168:169], v[166:167], v[168:169], s[50:51] op_sel_hi:[1,1,0]
	v_add_f32_e32 v171, 1.0, v171
	v_pk_fma_f32 v[162:163], v[160:161], v[162:163], s[52:53] op_sel_hi:[1,1,0]
	v_pk_fma_f32 v[168:169], v[166:167], v[168:169], s[52:53] op_sel_hi:[1,1,0]
	v_add_f32_e32 v172, 1.0, v172
	v_pk_fma_f32 v[160:161], v[160:161], v[162:163], s[54:55] op_sel_hi:[1,1,0]
	v_pk_fma_f32 v[166:167], v[166:167], v[168:169], s[54:55] op_sel_hi:[1,1,0]
	v_add_f32_e32 v173, 1.0, v173
	v_pk_fma_f32 v[158:159], v[158:159], v[160:161], 0.5 op_sel_hi:[1,1,0]
	v_pk_fma_f32 v[164:165], v[164:165], v[166:167], 0.5 op_sel_hi:[1,1,0]
	v_rcp_f32_e32 v178, v170
	v_pk_mul_f32 v[128:129], v[128:129], v[158:159]
	v_pk_mul_f32 v[130:131], v[130:131], v[164:165]
	v_rcp_f32_e32 v179, v171
	v_rcp_f32_e32 v180, v172
	v_rcp_f32_e32 v181, v173
	v_pk_mul_f32 v[124:125], v[124:125], v[178:179]
	v_pk_mul_f32 v[126:127], v[126:127], v[180:181]
	v_med3_f32 v158, v120, -4.0, 4.0
	v_med3_f32 v164, v122, -4.0, 4.0
	v_mul_f32_e32 v170, 0xbfb8aa3b, v116
	v_med3_f32 v159, v121, -4.0, 4.0
	v_med3_f32 v165, v123, -4.0, 4.0
	v_mul_f32_e32 v171, 0xbfb8aa3b, v117
	v_pk_mul_f32 v[160:161], v[158:159], v[158:159]
	v_pk_mul_f32 v[166:167], v[164:165], v[164:165]
	v_mul_f32_e32 v172, 0xbfb8aa3b, v118
	v_pk_fma_f32 v[160:161], v[160:161], s[72:73], -1.0 op_sel_hi:[1,0,0]
	v_pk_fma_f32 v[166:167], v[166:167], s[72:73], -1.0 op_sel_hi:[1,0,0]
	v_mul_f32_e32 v173, 0xbfb8aa3b, v119
	v_pk_fma_f32 v[162:163], v[160:161], s[74:75], v[198:199] op_sel_hi:[1,0,0]
	v_pk_fma_f32 v[168:169], v[166:167], s[74:75], v[198:199] op_sel_hi:[1,0,0]
	v_exp_f32_e32 v170, v170
	v_pk_fma_f32 v[162:163], v[160:161], v[162:163], s[2:3] op_sel_hi:[1,1,0]
	v_pk_fma_f32 v[168:169], v[166:167], v[168:169], s[2:3] op_sel_hi:[1,1,0]
	v_exp_f32_e32 v171, v171
	v_pk_fma_f32 v[162:163], v[160:161], v[162:163], s[28:29] op_sel_hi:[1,1,0]
	v_pk_fma_f32 v[168:169], v[166:167], v[168:169], s[28:29] op_sel_hi:[1,1,0]
	v_exp_f32_e32 v172, v172
	v_pk_fma_f32 v[162:163], v[160:161], v[162:163], s[30:31] op_sel_hi:[1,1,0]
	v_pk_fma_f32 v[168:169], v[166:167], v[168:169], s[30:31] op_sel_hi:[1,1,0]
	v_exp_f32_e32 v173, v173
	v_pk_fma_f32 v[162:163], v[160:161], v[162:163], s[48:49] op_sel_hi:[1,1,0]
	v_pk_fma_f32 v[168:169], v[166:167], v[168:169], s[48:49] op_sel_hi:[1,1,0]
	v_add_f32_e32 v170, 1.0, v170
	v_pk_fma_f32 v[162:163], v[160:161], v[162:163], s[50:51] op_sel_hi:[1,1,0]
	v_pk_fma_f32 v[168:169], v[166:167], v[168:169], s[50:51] op_sel_hi:[1,1,0]
	v_add_f32_e32 v171, 1.0, v171
	v_pk_fma_f32 v[162:163], v[160:161], v[162:163], s[52:53] op_sel_hi:[1,1,0]
	v_pk_fma_f32 v[168:169], v[166:167], v[168:169], s[52:53] op_sel_hi:[1,1,0]
	v_add_f32_e32 v172, 1.0, v172
	v_pk_fma_f32 v[160:161], v[160:161], v[162:163], s[54:55] op_sel_hi:[1,1,0]
	v_pk_fma_f32 v[166:167], v[166:167], v[168:169], s[54:55] op_sel_hi:[1,1,0]
	v_add_f32_e32 v173, 1.0, v173
	v_pk_fma_f32 v[158:159], v[158:159], v[160:161], 0.5 op_sel_hi:[1,1,0]
	v_pk_fma_f32 v[164:165], v[164:165], v[166:167], 0.5 op_sel_hi:[1,1,0]
	v_rcp_f32_e32 v178, v170
	v_pk_mul_f32 v[120:121], v[120:121], v[158:159]
	v_pk_mul_f32 v[122:123], v[122:123], v[164:165]
	v_rcp_f32_e32 v179, v171
	v_rcp_f32_e32 v180, v172
	v_rcp_f32_e32 v181, v173
	v_pk_mul_f32 v[116:117], v[116:117], v[178:179]
	v_pk_mul_f32 v[118:119], v[118:119], v[180:181]
	v_pk_mul_f32 v[124:125], v[124:125], v[128:129]
	v_pk_mul_f32 v[126:127], v[126:127], v[130:131]
	v_pk_mul_f32 v[116:117], v[116:117], v[120:121]
	v_pk_mul_f32 v[118:119], v[118:119], v[122:123]
	v_cvt_pk_bf16_f32 v128, v124, v125
	v_cvt_pk_bf16_f32 v129, v126, v127
	v_cvt_pk_bf16_f32 v130, v116, v117
	v_cvt_pk_bf16_f32 v131, v118, v119
	global_store_dwordx4 v182, v[128:131], s[10:11]
	v_pk_mul_f32 v[112:113], v[112:113], v[202:203] op_sel_hi:[1,0]
	v_pk_mul_f32 v[114:115], v[114:115], v[202:203] op_sel_hi:[1,0]
	v_pk_mul_f32 v[104:105], v[104:105], v[202:203] op_sel_hi:[1,0]
	v_pk_mul_f32 v[106:107], v[106:107], v[202:203] op_sel_hi:[1,0]
	v_pk_mul_f32 v[108:109], v[108:109], v[202:203] op_sel_hi:[1,0]
	v_pk_mul_f32 v[110:111], v[110:111], v[202:203] op_sel_hi:[1,0]
	v_pk_mul_f32 v[100:101], v[100:101], v[202:203] op_sel_hi:[1,0]
	v_pk_mul_f32 v[102:103], v[102:103], v[202:203] op_sel_hi:[1,0]
	v_med3_f32 v158, v112, -4.0, 4.0
	v_med3_f32 v164, v114, -4.0, 4.0
	v_mul_f32_e32 v170, 0xbfb8aa3b, v108
	v_med3_f32 v159, v113, -4.0, 4.0
	v_med3_f32 v165, v115, -4.0, 4.0
	v_mul_f32_e32 v171, 0xbfb8aa3b, v109
	v_pk_mul_f32 v[160:161], v[158:159], v[158:159]
	v_pk_mul_f32 v[166:167], v[164:165], v[164:165]
	v_mul_f32_e32 v172, 0xbfb8aa3b, v110
	v_pk_fma_f32 v[160:161], v[160:161], s[72:73], -1.0 op_sel_hi:[1,0,0]
	v_pk_fma_f32 v[166:167], v[166:167], s[72:73], -1.0 op_sel_hi:[1,0,0]
	v_mul_f32_e32 v173, 0xbfb8aa3b, v111
	v_pk_fma_f32 v[162:163], v[160:161], s[74:75], v[198:199] op_sel_hi:[1,0,0]
	v_pk_fma_f32 v[168:169], v[166:167], s[74:75], v[198:199] op_sel_hi:[1,0,0]
	v_exp_f32_e32 v170, v170
	v_pk_fma_f32 v[162:163], v[160:161], v[162:163], s[2:3] op_sel_hi:[1,1,0]
	v_pk_fma_f32 v[168:169], v[166:167], v[168:169], s[2:3] op_sel_hi:[1,1,0]
	v_exp_f32_e32 v171, v171
	v_pk_fma_f32 v[162:163], v[160:161], v[162:163], s[28:29] op_sel_hi:[1,1,0]
	v_pk_fma_f32 v[168:169], v[166:167], v[168:169], s[28:29] op_sel_hi:[1,1,0]
	v_exp_f32_e32 v172, v172
	v_pk_fma_f32 v[162:163], v[160:161], v[162:163], s[30:31] op_sel_hi:[1,1,0]
	v_pk_fma_f32 v[168:169], v[166:167], v[168:169], s[30:31] op_sel_hi:[1,1,0]
	v_exp_f32_e32 v173, v173
	v_pk_fma_f32 v[162:163], v[160:161], v[162:163], s[48:49] op_sel_hi:[1,1,0]
	v_pk_fma_f32 v[168:169], v[166:167], v[168:169], s[48:49] op_sel_hi:[1,1,0]
	v_add_f32_e32 v170, 1.0, v170
	v_pk_fma_f32 v[162:163], v[160:161], v[162:163], s[50:51] op_sel_hi:[1,1,0]
	v_pk_fma_f32 v[168:169], v[166:167], v[168:169], s[50:51] op_sel_hi:[1,1,0]
	v_add_f32_e32 v171, 1.0, v171
	v_pk_fma_f32 v[162:163], v[160:161], v[162:163], s[52:53] op_sel_hi:[1,1,0]
	v_pk_fma_f32 v[168:169], v[166:167], v[168:169], s[52:53] op_sel_hi:[1,1,0]
	v_add_f32_e32 v172, 1.0, v172
	v_pk_fma_f32 v[160:161], v[160:161], v[162:163], s[54:55] op_sel_hi:[1,1,0]
	v_pk_fma_f32 v[166:167], v[166:167], v[168:169], s[54:55] op_sel_hi:[1,1,0]
	v_add_f32_e32 v173, 1.0, v173
	v_pk_fma_f32 v[158:159], v[158:159], v[160:161], 0.5 op_sel_hi:[1,1,0]
	v_pk_fma_f32 v[164:165], v[164:165], v[166:167], 0.5 op_sel_hi:[1,1,0]
	v_rcp_f32_e32 v178, v170
	v_pk_mul_f32 v[112:113], v[112:113], v[158:159]
	v_pk_mul_f32 v[114:115], v[114:115], v[164:165]
	v_rcp_f32_e32 v179, v171
	v_rcp_f32_e32 v180, v172
	v_rcp_f32_e32 v181, v173
	v_pk_mul_f32 v[108:109], v[108:109], v[178:179]
	v_pk_mul_f32 v[110:111], v[110:111], v[180:181]
	v_med3_f32 v158, v104, -4.0, 4.0
	v_med3_f32 v164, v106, -4.0, 4.0
	v_mul_f32_e32 v170, 0xbfb8aa3b, v100
	v_med3_f32 v159, v105, -4.0, 4.0
	v_med3_f32 v165, v107, -4.0, 4.0
	v_mul_f32_e32 v171, 0xbfb8aa3b, v101
	v_pk_mul_f32 v[160:161], v[158:159], v[158:159]
	v_pk_mul_f32 v[166:167], v[164:165], v[164:165]
	v_mul_f32_e32 v172, 0xbfb8aa3b, v102
	v_pk_fma_f32 v[160:161], v[160:161], s[72:73], -1.0 op_sel_hi:[1,0,0]
	v_pk_fma_f32 v[166:167], v[166:167], s[72:73], -1.0 op_sel_hi:[1,0,0]
	v_mul_f32_e32 v173, 0xbfb8aa3b, v103
	v_pk_fma_f32 v[162:163], v[160:161], s[74:75], v[198:199] op_sel_hi:[1,0,0]
	v_pk_fma_f32 v[168:169], v[166:167], s[74:75], v[198:199] op_sel_hi:[1,0,0]
	v_exp_f32_e32 v170, v170
	v_pk_fma_f32 v[162:163], v[160:161], v[162:163], s[2:3] op_sel_hi:[1,1,0]
	v_pk_fma_f32 v[168:169], v[166:167], v[168:169], s[2:3] op_sel_hi:[1,1,0]
	v_exp_f32_e32 v171, v171
	v_pk_fma_f32 v[162:163], v[160:161], v[162:163], s[28:29] op_sel_hi:[1,1,0]
	v_pk_fma_f32 v[168:169], v[166:167], v[168:169], s[28:29] op_sel_hi:[1,1,0]
	v_exp_f32_e32 v172, v172
	v_pk_fma_f32 v[162:163], v[160:161], v[162:163], s[30:31] op_sel_hi:[1,1,0]
	v_pk_fma_f32 v[168:169], v[166:167], v[168:169], s[30:31] op_sel_hi:[1,1,0]
	v_exp_f32_e32 v173, v173
	v_pk_fma_f32 v[162:163], v[160:161], v[162:163], s[48:49] op_sel_hi:[1,1,0]
	v_pk_fma_f32 v[168:169], v[166:167], v[168:169], s[48:49] op_sel_hi:[1,1,0]
	v_add_f32_e32 v170, 1.0, v170
	v_pk_fma_f32 v[162:163], v[160:161], v[162:163], s[50:51] op_sel_hi:[1,1,0]
	v_pk_fma_f32 v[168:169], v[166:167], v[168:169], s[50:51] op_sel_hi:[1,1,0]
	v_add_f32_e32 v171, 1.0, v171
	v_pk_fma_f32 v[162:163], v[160:161], v[162:163], s[52:53] op_sel_hi:[1,1,0]
	v_pk_fma_f32 v[168:169], v[166:167], v[168:169], s[52:53] op_sel_hi:[1,1,0]
	v_add_f32_e32 v172, 1.0, v172
	v_pk_fma_f32 v[160:161], v[160:161], v[162:163], s[54:55] op_sel_hi:[1,1,0]
	v_pk_fma_f32 v[166:167], v[166:167], v[168:169], s[54:55] op_sel_hi:[1,1,0]
	v_add_f32_e32 v173, 1.0, v173
	v_pk_fma_f32 v[158:159], v[158:159], v[160:161], 0.5 op_sel_hi:[1,1,0]
	v_pk_fma_f32 v[164:165], v[164:165], v[166:167], 0.5 op_sel_hi:[1,1,0]
	v_rcp_f32_e32 v178, v170
	v_pk_mul_f32 v[104:105], v[104:105], v[158:159]
	v_pk_mul_f32 v[106:107], v[106:107], v[164:165]
	v_rcp_f32_e32 v179, v171
	v_rcp_f32_e32 v180, v172
	v_rcp_f32_e32 v181, v173
	v_pk_mul_f32 v[100:101], v[100:101], v[178:179]
	v_pk_mul_f32 v[102:103], v[102:103], v[180:181]
	v_pk_mul_f32 v[108:109], v[108:109], v[112:113]
	v_pk_mul_f32 v[110:111], v[110:111], v[114:115]
	v_pk_mul_f32 v[100:101], v[100:101], v[104:105]
	v_pk_mul_f32 v[102:103], v[102:103], v[106:107]
	v_cvt_pk_bf16_f32 v112, v108, v109
	v_cvt_pk_bf16_f32 v113, v110, v111
	v_cvt_pk_bf16_f32 v114, v100, v101
	v_cvt_pk_bf16_f32 v115, v102, v103
	global_store_dwordx4 v183, v[112:115], s[10:11]
	v_pk_mul_f32 v[96:97], v[96:97], v[204:205] op_sel_hi:[1,0]
	v_pk_mul_f32 v[98:99], v[98:99], v[204:205] op_sel_hi:[1,0]
	v_pk_mul_f32 v[88:89], v[88:89], v[204:205] op_sel_hi:[1,0]
	v_pk_mul_f32 v[90:91], v[90:91], v[204:205] op_sel_hi:[1,0]
	v_pk_mul_f32 v[92:93], v[92:93], v[204:205] op_sel_hi:[1,0]
	v_pk_mul_f32 v[94:95], v[94:95], v[204:205] op_sel_hi:[1,0]
	v_pk_mul_f32 v[84:85], v[84:85], v[204:205] op_sel_hi:[1,0]
	v_pk_mul_f32 v[86:87], v[86:87], v[204:205] op_sel_hi:[1,0]
	v_med3_f32 v158, v96, -4.0, 4.0
	v_med3_f32 v164, v98, -4.0, 4.0
	v_mul_f32_e32 v170, 0xbfb8aa3b, v92
	v_med3_f32 v159, v97, -4.0, 4.0
	v_med3_f32 v165, v99, -4.0, 4.0
	v_mul_f32_e32 v171, 0xbfb8aa3b, v93
	v_pk_mul_f32 v[160:161], v[158:159], v[158:159]
	v_pk_mul_f32 v[166:167], v[164:165], v[164:165]
	v_mul_f32_e32 v172, 0xbfb8aa3b, v94
	v_pk_fma_f32 v[160:161], v[160:161], s[72:73], -1.0 op_sel_hi:[1,0,0]
	v_pk_fma_f32 v[166:167], v[166:167], s[72:73], -1.0 op_sel_hi:[1,0,0]
	v_mul_f32_e32 v173, 0xbfb8aa3b, v95
	v_pk_fma_f32 v[162:163], v[160:161], s[74:75], v[198:199] op_sel_hi:[1,0,0]
	v_pk_fma_f32 v[168:169], v[166:167], s[74:75], v[198:199] op_sel_hi:[1,0,0]
	v_exp_f32_e32 v170, v170
	v_pk_fma_f32 v[162:163], v[160:161], v[162:163], s[2:3] op_sel_hi:[1,1,0]
	v_pk_fma_f32 v[168:169], v[166:167], v[168:169], s[2:3] op_sel_hi:[1,1,0]
	v_exp_f32_e32 v171, v171
	v_pk_fma_f32 v[162:163], v[160:161], v[162:163], s[28:29] op_sel_hi:[1,1,0]
	v_pk_fma_f32 v[168:169], v[166:167], v[168:169], s[28:29] op_sel_hi:[1,1,0]
	v_exp_f32_e32 v172, v172
	v_pk_fma_f32 v[162:163], v[160:161], v[162:163], s[30:31] op_sel_hi:[1,1,0]
	v_pk_fma_f32 v[168:169], v[166:167], v[168:169], s[30:31] op_sel_hi:[1,1,0]
	v_exp_f32_e32 v173, v173
	v_pk_fma_f32 v[162:163], v[160:161], v[162:163], s[48:49] op_sel_hi:[1,1,0]
	v_pk_fma_f32 v[168:169], v[166:167], v[168:169], s[48:49] op_sel_hi:[1,1,0]
	v_add_f32_e32 v170, 1.0, v170
	v_pk_fma_f32 v[162:163], v[160:161], v[162:163], s[50:51] op_sel_hi:[1,1,0]
	v_pk_fma_f32 v[168:169], v[166:167], v[168:169], s[50:51] op_sel_hi:[1,1,0]
	v_add_f32_e32 v171, 1.0, v171
	v_pk_fma_f32 v[162:163], v[160:161], v[162:163], s[52:53] op_sel_hi:[1,1,0]
	v_pk_fma_f32 v[168:169], v[166:167], v[168:169], s[52:53] op_sel_hi:[1,1,0]
	v_add_f32_e32 v172, 1.0, v172
	v_pk_fma_f32 v[160:161], v[160:161], v[162:163], s[54:55] op_sel_hi:[1,1,0]
	v_pk_fma_f32 v[166:167], v[166:167], v[168:169], s[54:55] op_sel_hi:[1,1,0]
	v_add_f32_e32 v173, 1.0, v173
	v_pk_fma_f32 v[158:159], v[158:159], v[160:161], 0.5 op_sel_hi:[1,1,0]
	v_pk_fma_f32 v[164:165], v[164:165], v[166:167], 0.5 op_sel_hi:[1,1,0]
	v_rcp_f32_e32 v178, v170
	v_pk_mul_f32 v[96:97], v[96:97], v[158:159]
	v_pk_mul_f32 v[98:99], v[98:99], v[164:165]
	v_rcp_f32_e32 v179, v171
	v_rcp_f32_e32 v180, v172
	v_rcp_f32_e32 v181, v173
	v_pk_mul_f32 v[92:93], v[92:93], v[178:179]
	v_pk_mul_f32 v[94:95], v[94:95], v[180:181]
	v_med3_f32 v158, v88, -4.0, 4.0
	v_med3_f32 v164, v90, -4.0, 4.0
	v_mul_f32_e32 v170, 0xbfb8aa3b, v84
	v_med3_f32 v159, v89, -4.0, 4.0
	v_med3_f32 v165, v91, -4.0, 4.0
	v_mul_f32_e32 v171, 0xbfb8aa3b, v85
	v_pk_mul_f32 v[160:161], v[158:159], v[158:159]
	v_pk_mul_f32 v[166:167], v[164:165], v[164:165]
	v_mul_f32_e32 v172, 0xbfb8aa3b, v86
	v_pk_fma_f32 v[160:161], v[160:161], s[72:73], -1.0 op_sel_hi:[1,0,0]
	v_pk_fma_f32 v[166:167], v[166:167], s[72:73], -1.0 op_sel_hi:[1,0,0]
	v_mul_f32_e32 v173, 0xbfb8aa3b, v87
	v_pk_fma_f32 v[162:163], v[160:161], s[74:75], v[198:199] op_sel_hi:[1,0,0]
	v_pk_fma_f32 v[168:169], v[166:167], s[74:75], v[198:199] op_sel_hi:[1,0,0]
	v_exp_f32_e32 v170, v170
	v_pk_fma_f32 v[162:163], v[160:161], v[162:163], s[2:3] op_sel_hi:[1,1,0]
	v_pk_fma_f32 v[168:169], v[166:167], v[168:169], s[2:3] op_sel_hi:[1,1,0]
	v_exp_f32_e32 v171, v171
	v_pk_fma_f32 v[162:163], v[160:161], v[162:163], s[28:29] op_sel_hi:[1,1,0]
	v_pk_fma_f32 v[168:169], v[166:167], v[168:169], s[28:29] op_sel_hi:[1,1,0]
	v_exp_f32_e32 v172, v172
	v_pk_fma_f32 v[162:163], v[160:161], v[162:163], s[30:31] op_sel_hi:[1,1,0]
	v_pk_fma_f32 v[168:169], v[166:167], v[168:169], s[30:31] op_sel_hi:[1,1,0]
	v_exp_f32_e32 v173, v173
	v_pk_fma_f32 v[162:163], v[160:161], v[162:163], s[48:49] op_sel_hi:[1,1,0]
	v_pk_fma_f32 v[168:169], v[166:167], v[168:169], s[48:49] op_sel_hi:[1,1,0]
	v_add_f32_e32 v170, 1.0, v170
	v_pk_fma_f32 v[162:163], v[160:161], v[162:163], s[50:51] op_sel_hi:[1,1,0]
	v_pk_fma_f32 v[168:169], v[166:167], v[168:169], s[50:51] op_sel_hi:[1,1,0]
	v_add_f32_e32 v171, 1.0, v171
	v_pk_fma_f32 v[162:163], v[160:161], v[162:163], s[52:53] op_sel_hi:[1,1,0]
	v_pk_fma_f32 v[168:169], v[166:167], v[168:169], s[52:53] op_sel_hi:[1,1,0]
	v_add_f32_e32 v172, 1.0, v172
	v_pk_fma_f32 v[160:161], v[160:161], v[162:163], s[54:55] op_sel_hi:[1,1,0]
	v_pk_fma_f32 v[166:167], v[166:167], v[168:169], s[54:55] op_sel_hi:[1,1,0]
	v_add_f32_e32 v173, 1.0, v173
	v_pk_fma_f32 v[158:159], v[158:159], v[160:161], 0.5 op_sel_hi:[1,1,0]
	v_pk_fma_f32 v[164:165], v[164:165], v[166:167], 0.5 op_sel_hi:[1,1,0]
	v_rcp_f32_e32 v178, v170
	v_pk_mul_f32 v[88:89], v[88:89], v[158:159]
	v_pk_mul_f32 v[90:91], v[90:91], v[164:165]
	v_rcp_f32_e32 v179, v171
	v_rcp_f32_e32 v180, v172
	v_rcp_f32_e32 v181, v173
	v_pk_mul_f32 v[84:85], v[84:85], v[178:179]
	v_pk_mul_f32 v[86:87], v[86:87], v[180:181]
	v_pk_mul_f32 v[92:93], v[92:93], v[96:97]
	v_pk_mul_f32 v[94:95], v[94:95], v[98:99]
	v_pk_mul_f32 v[84:85], v[84:85], v[88:89]
	v_pk_mul_f32 v[86:87], v[86:87], v[90:91]
	v_cvt_pk_bf16_f32 v96, v92, v93
	v_cvt_pk_bf16_f32 v97, v94, v95
	v_cvt_pk_bf16_f32 v98, v84, v85
	v_cvt_pk_bf16_f32 v99, v86, v87
	global_store_dwordx4 v184, v[96:99], s[10:11]
	v_pk_mul_f32 v[80:81], v[80:81], v[206:207] op_sel_hi:[1,0]
	v_pk_mul_f32 v[82:83], v[82:83], v[206:207] op_sel_hi:[1,0]
	v_pk_mul_f32 v[72:73], v[72:73], v[206:207] op_sel_hi:[1,0]
	v_pk_mul_f32 v[74:75], v[74:75], v[206:207] op_sel_hi:[1,0]
	v_pk_mul_f32 v[76:77], v[76:77], v[206:207] op_sel_hi:[1,0]
	v_pk_mul_f32 v[78:79], v[78:79], v[206:207] op_sel_hi:[1,0]
	v_pk_mul_f32 v[68:69], v[68:69], v[206:207] op_sel_hi:[1,0]
	v_pk_mul_f32 v[70:71], v[70:71], v[206:207] op_sel_hi:[1,0]
	v_med3_f32 v158, v80, -4.0, 4.0
	v_med3_f32 v164, v82, -4.0, 4.0
	v_mul_f32_e32 v170, 0xbfb8aa3b, v76
	v_med3_f32 v159, v81, -4.0, 4.0
	v_med3_f32 v165, v83, -4.0, 4.0
	v_mul_f32_e32 v171, 0xbfb8aa3b, v77
	v_pk_mul_f32 v[160:161], v[158:159], v[158:159]
	v_pk_mul_f32 v[166:167], v[164:165], v[164:165]
	v_mul_f32_e32 v172, 0xbfb8aa3b, v78
	v_pk_fma_f32 v[160:161], v[160:161], s[72:73], -1.0 op_sel_hi:[1,0,0]
	v_pk_fma_f32 v[166:167], v[166:167], s[72:73], -1.0 op_sel_hi:[1,0,0]
	v_mul_f32_e32 v173, 0xbfb8aa3b, v79
	v_pk_fma_f32 v[162:163], v[160:161], s[74:75], v[198:199] op_sel_hi:[1,0,0]
	v_pk_fma_f32 v[168:169], v[166:167], s[74:75], v[198:199] op_sel_hi:[1,0,0]
	v_exp_f32_e32 v170, v170
	v_pk_fma_f32 v[162:163], v[160:161], v[162:163], s[2:3] op_sel_hi:[1,1,0]
	v_pk_fma_f32 v[168:169], v[166:167], v[168:169], s[2:3] op_sel_hi:[1,1,0]
	v_exp_f32_e32 v171, v171
	v_pk_fma_f32 v[162:163], v[160:161], v[162:163], s[28:29] op_sel_hi:[1,1,0]
	v_pk_fma_f32 v[168:169], v[166:167], v[168:169], s[28:29] op_sel_hi:[1,1,0]
	v_exp_f32_e32 v172, v172
	v_pk_fma_f32 v[162:163], v[160:161], v[162:163], s[30:31] op_sel_hi:[1,1,0]
	v_pk_fma_f32 v[168:169], v[166:167], v[168:169], s[30:31] op_sel_hi:[1,1,0]
	v_exp_f32_e32 v173, v173
	v_pk_fma_f32 v[162:163], v[160:161], v[162:163], s[48:49] op_sel_hi:[1,1,0]
	v_pk_fma_f32 v[168:169], v[166:167], v[168:169], s[48:49] op_sel_hi:[1,1,0]
	v_add_f32_e32 v170, 1.0, v170
	v_pk_fma_f32 v[162:163], v[160:161], v[162:163], s[50:51] op_sel_hi:[1,1,0]
	v_pk_fma_f32 v[168:169], v[166:167], v[168:169], s[50:51] op_sel_hi:[1,1,0]
	v_add_f32_e32 v171, 1.0, v171
	v_pk_fma_f32 v[162:163], v[160:161], v[162:163], s[52:53] op_sel_hi:[1,1,0]
	v_pk_fma_f32 v[168:169], v[166:167], v[168:169], s[52:53] op_sel_hi:[1,1,0]
	v_add_f32_e32 v172, 1.0, v172
	v_pk_fma_f32 v[160:161], v[160:161], v[162:163], s[54:55] op_sel_hi:[1,1,0]
	v_pk_fma_f32 v[166:167], v[166:167], v[168:169], s[54:55] op_sel_hi:[1,1,0]
	v_add_f32_e32 v173, 1.0, v173
	v_pk_fma_f32 v[158:159], v[158:159], v[160:161], 0.5 op_sel_hi:[1,1,0]
	v_pk_fma_f32 v[164:165], v[164:165], v[166:167], 0.5 op_sel_hi:[1,1,0]
	v_rcp_f32_e32 v178, v170
	v_pk_mul_f32 v[80:81], v[80:81], v[158:159]
	v_pk_mul_f32 v[82:83], v[82:83], v[164:165]
	v_rcp_f32_e32 v179, v171
	v_rcp_f32_e32 v180, v172
	v_rcp_f32_e32 v181, v173
	v_pk_mul_f32 v[76:77], v[76:77], v[178:179]
	v_pk_mul_f32 v[78:79], v[78:79], v[180:181]
	v_med3_f32 v158, v72, -4.0, 4.0
	v_med3_f32 v164, v74, -4.0, 4.0
	v_mul_f32_e32 v170, 0xbfb8aa3b, v68
	v_med3_f32 v159, v73, -4.0, 4.0
	v_med3_f32 v165, v75, -4.0, 4.0
	v_mul_f32_e32 v171, 0xbfb8aa3b, v69
	v_pk_mul_f32 v[160:161], v[158:159], v[158:159]
	v_pk_mul_f32 v[166:167], v[164:165], v[164:165]
	v_mul_f32_e32 v172, 0xbfb8aa3b, v70
	v_pk_fma_f32 v[160:161], v[160:161], s[72:73], -1.0 op_sel_hi:[1,0,0]
	v_pk_fma_f32 v[166:167], v[166:167], s[72:73], -1.0 op_sel_hi:[1,0,0]
	v_mul_f32_e32 v173, 0xbfb8aa3b, v71
	v_pk_fma_f32 v[162:163], v[160:161], s[74:75], v[198:199] op_sel_hi:[1,0,0]
	v_pk_fma_f32 v[168:169], v[166:167], s[74:75], v[198:199] op_sel_hi:[1,0,0]
	v_exp_f32_e32 v170, v170
	v_pk_fma_f32 v[162:163], v[160:161], v[162:163], s[2:3] op_sel_hi:[1,1,0]
	v_pk_fma_f32 v[168:169], v[166:167], v[168:169], s[2:3] op_sel_hi:[1,1,0]
	v_exp_f32_e32 v171, v171
	v_pk_fma_f32 v[162:163], v[160:161], v[162:163], s[28:29] op_sel_hi:[1,1,0]
	v_pk_fma_f32 v[168:169], v[166:167], v[168:169], s[28:29] op_sel_hi:[1,1,0]
	v_exp_f32_e32 v172, v172
	v_pk_fma_f32 v[162:163], v[160:161], v[162:163], s[30:31] op_sel_hi:[1,1,0]
	v_pk_fma_f32 v[168:169], v[166:167], v[168:169], s[30:31] op_sel_hi:[1,1,0]
	v_exp_f32_e32 v173, v173
	v_pk_fma_f32 v[162:163], v[160:161], v[162:163], s[48:49] op_sel_hi:[1,1,0]
	v_pk_fma_f32 v[168:169], v[166:167], v[168:169], s[48:49] op_sel_hi:[1,1,0]
	v_add_f32_e32 v170, 1.0, v170
	v_pk_fma_f32 v[162:163], v[160:161], v[162:163], s[50:51] op_sel_hi:[1,1,0]
	v_pk_fma_f32 v[168:169], v[166:167], v[168:169], s[50:51] op_sel_hi:[1,1,0]
	v_add_f32_e32 v171, 1.0, v171
	v_pk_fma_f32 v[162:163], v[160:161], v[162:163], s[52:53] op_sel_hi:[1,1,0]
	v_pk_fma_f32 v[168:169], v[166:167], v[168:169], s[52:53] op_sel_hi:[1,1,0]
	v_add_f32_e32 v172, 1.0, v172
	v_pk_fma_f32 v[160:161], v[160:161], v[162:163], s[54:55] op_sel_hi:[1,1,0]
	v_pk_fma_f32 v[166:167], v[166:167], v[168:169], s[54:55] op_sel_hi:[1,1,0]
	v_add_f32_e32 v173, 1.0, v173
	v_pk_fma_f32 v[158:159], v[158:159], v[160:161], 0.5 op_sel_hi:[1,1,0]
	v_pk_fma_f32 v[164:165], v[164:165], v[166:167], 0.5 op_sel_hi:[1,1,0]
	v_rcp_f32_e32 v178, v170
	v_pk_mul_f32 v[72:73], v[72:73], v[158:159]
	v_pk_mul_f32 v[74:75], v[74:75], v[164:165]
	v_rcp_f32_e32 v179, v171
	v_rcp_f32_e32 v180, v172
	v_rcp_f32_e32 v181, v173
	v_pk_mul_f32 v[68:69], v[68:69], v[178:179]
	v_pk_mul_f32 v[70:71], v[70:71], v[180:181]
	v_pk_mul_f32 v[76:77], v[76:77], v[80:81]
	v_pk_mul_f32 v[78:79], v[78:79], v[82:83]
	v_pk_mul_f32 v[68:69], v[68:69], v[72:73]
	v_pk_mul_f32 v[70:71], v[70:71], v[74:75]
	v_cvt_pk_bf16_f32 v80, v76, v77
	v_cvt_pk_bf16_f32 v81, v78, v79
	v_cvt_pk_bf16_f32 v82, v68, v69
	v_cvt_pk_bf16_f32 v83, v70, v71
	global_store_dwordx4 v185, v[80:83], s[10:11]
	v_pk_mul_f32 v[64:65], v[64:65], v[208:209] op_sel_hi:[1,0]
	v_pk_mul_f32 v[66:67], v[66:67], v[208:209] op_sel_hi:[1,0]
	v_pk_mul_f32 v[56:57], v[56:57], v[208:209] op_sel_hi:[1,0]
	v_pk_mul_f32 v[58:59], v[58:59], v[208:209] op_sel_hi:[1,0]
	v_pk_mul_f32 v[60:61], v[60:61], v[208:209] op_sel_hi:[1,0]
	v_pk_mul_f32 v[62:63], v[62:63], v[208:209] op_sel_hi:[1,0]
	v_pk_mul_f32 v[52:53], v[52:53], v[208:209] op_sel_hi:[1,0]
	v_pk_mul_f32 v[54:55], v[54:55], v[208:209] op_sel_hi:[1,0]
	v_med3_f32 v158, v64, -4.0, 4.0
	v_med3_f32 v164, v66, -4.0, 4.0
	v_mul_f32_e32 v170, 0xbfb8aa3b, v60
	v_med3_f32 v159, v65, -4.0, 4.0
	v_med3_f32 v165, v67, -4.0, 4.0
	v_mul_f32_e32 v171, 0xbfb8aa3b, v61
	v_pk_mul_f32 v[160:161], v[158:159], v[158:159]
	v_pk_mul_f32 v[166:167], v[164:165], v[164:165]
	v_mul_f32_e32 v172, 0xbfb8aa3b, v62
	v_pk_fma_f32 v[160:161], v[160:161], s[72:73], -1.0 op_sel_hi:[1,0,0]
	v_pk_fma_f32 v[166:167], v[166:167], s[72:73], -1.0 op_sel_hi:[1,0,0]
	v_mul_f32_e32 v173, 0xbfb8aa3b, v63
	v_pk_fma_f32 v[162:163], v[160:161], s[74:75], v[198:199] op_sel_hi:[1,0,0]
	v_pk_fma_f32 v[168:169], v[166:167], s[74:75], v[198:199] op_sel_hi:[1,0,0]
	v_exp_f32_e32 v170, v170
	v_pk_fma_f32 v[162:163], v[160:161], v[162:163], s[2:3] op_sel_hi:[1,1,0]
	v_pk_fma_f32 v[168:169], v[166:167], v[168:169], s[2:3] op_sel_hi:[1,1,0]
	v_exp_f32_e32 v171, v171
	v_pk_fma_f32 v[162:163], v[160:161], v[162:163], s[28:29] op_sel_hi:[1,1,0]
	v_pk_fma_f32 v[168:169], v[166:167], v[168:169], s[28:29] op_sel_hi:[1,1,0]
	v_exp_f32_e32 v172, v172
	v_pk_fma_f32 v[162:163], v[160:161], v[162:163], s[30:31] op_sel_hi:[1,1,0]
	v_pk_fma_f32 v[168:169], v[166:167], v[168:169], s[30:31] op_sel_hi:[1,1,0]
	v_exp_f32_e32 v173, v173
	v_pk_fma_f32 v[162:163], v[160:161], v[162:163], s[48:49] op_sel_hi:[1,1,0]
	v_pk_fma_f32 v[168:169], v[166:167], v[168:169], s[48:49] op_sel_hi:[1,1,0]
	v_add_f32_e32 v170, 1.0, v170
	v_pk_fma_f32 v[162:163], v[160:161], v[162:163], s[50:51] op_sel_hi:[1,1,0]
	v_pk_fma_f32 v[168:169], v[166:167], v[168:169], s[50:51] op_sel_hi:[1,1,0]
	v_add_f32_e32 v171, 1.0, v171
	v_pk_fma_f32 v[162:163], v[160:161], v[162:163], s[52:53] op_sel_hi:[1,1,0]
	v_pk_fma_f32 v[168:169], v[166:167], v[168:169], s[52:53] op_sel_hi:[1,1,0]
	v_add_f32_e32 v172, 1.0, v172
	v_pk_fma_f32 v[160:161], v[160:161], v[162:163], s[54:55] op_sel_hi:[1,1,0]
	v_pk_fma_f32 v[166:167], v[166:167], v[168:169], s[54:55] op_sel_hi:[1,1,0]
	v_add_f32_e32 v173, 1.0, v173
	v_pk_fma_f32 v[158:159], v[158:159], v[160:161], 0.5 op_sel_hi:[1,1,0]
	v_pk_fma_f32 v[164:165], v[164:165], v[166:167], 0.5 op_sel_hi:[1,1,0]
	v_rcp_f32_e32 v178, v170
	v_pk_mul_f32 v[64:65], v[64:65], v[158:159]
	v_pk_mul_f32 v[66:67], v[66:67], v[164:165]
	v_rcp_f32_e32 v179, v171
	v_rcp_f32_e32 v180, v172
	v_rcp_f32_e32 v181, v173
	v_pk_mul_f32 v[60:61], v[60:61], v[178:179]
	v_pk_mul_f32 v[62:63], v[62:63], v[180:181]
	v_med3_f32 v158, v56, -4.0, 4.0
	v_med3_f32 v164, v58, -4.0, 4.0
	v_mul_f32_e32 v170, 0xbfb8aa3b, v52
	v_med3_f32 v159, v57, -4.0, 4.0
	v_med3_f32 v165, v59, -4.0, 4.0
	v_mul_f32_e32 v171, 0xbfb8aa3b, v53
	v_pk_mul_f32 v[160:161], v[158:159], v[158:159]
	v_pk_mul_f32 v[166:167], v[164:165], v[164:165]
	v_mul_f32_e32 v172, 0xbfb8aa3b, v54
	v_pk_fma_f32 v[160:161], v[160:161], s[72:73], -1.0 op_sel_hi:[1,0,0]
	v_pk_fma_f32 v[166:167], v[166:167], s[72:73], -1.0 op_sel_hi:[1,0,0]
	v_mul_f32_e32 v173, 0xbfb8aa3b, v55
	v_pk_fma_f32 v[162:163], v[160:161], s[74:75], v[198:199] op_sel_hi:[1,0,0]
	v_pk_fma_f32 v[168:169], v[166:167], s[74:75], v[198:199] op_sel_hi:[1,0,0]
	v_exp_f32_e32 v170, v170
	v_pk_fma_f32 v[162:163], v[160:161], v[162:163], s[2:3] op_sel_hi:[1,1,0]
	v_pk_fma_f32 v[168:169], v[166:167], v[168:169], s[2:3] op_sel_hi:[1,1,0]
	v_exp_f32_e32 v171, v171
	v_pk_fma_f32 v[162:163], v[160:161], v[162:163], s[28:29] op_sel_hi:[1,1,0]
	v_pk_fma_f32 v[168:169], v[166:167], v[168:169], s[28:29] op_sel_hi:[1,1,0]
	v_exp_f32_e32 v172, v172
	v_pk_fma_f32 v[162:163], v[160:161], v[162:163], s[30:31] op_sel_hi:[1,1,0]
	v_pk_fma_f32 v[168:169], v[166:167], v[168:169], s[30:31] op_sel_hi:[1,1,0]
	v_exp_f32_e32 v173, v173
	v_pk_fma_f32 v[162:163], v[160:161], v[162:163], s[48:49] op_sel_hi:[1,1,0]
	v_pk_fma_f32 v[168:169], v[166:167], v[168:169], s[48:49] op_sel_hi:[1,1,0]
	v_add_f32_e32 v170, 1.0, v170
	v_pk_fma_f32 v[162:163], v[160:161], v[162:163], s[50:51] op_sel_hi:[1,1,0]
	v_pk_fma_f32 v[168:169], v[166:167], v[168:169], s[50:51] op_sel_hi:[1,1,0]
	v_add_f32_e32 v171, 1.0, v171
	v_pk_fma_f32 v[162:163], v[160:161], v[162:163], s[52:53] op_sel_hi:[1,1,0]
	v_pk_fma_f32 v[168:169], v[166:167], v[168:169], s[52:53] op_sel_hi:[1,1,0]
	v_add_f32_e32 v172, 1.0, v172
	v_pk_fma_f32 v[160:161], v[160:161], v[162:163], s[54:55] op_sel_hi:[1,1,0]
	v_pk_fma_f32 v[166:167], v[166:167], v[168:169], s[54:55] op_sel_hi:[1,1,0]
	v_add_f32_e32 v173, 1.0, v173
	v_pk_fma_f32 v[158:159], v[158:159], v[160:161], 0.5 op_sel_hi:[1,1,0]
	v_pk_fma_f32 v[164:165], v[164:165], v[166:167], 0.5 op_sel_hi:[1,1,0]
	v_rcp_f32_e32 v178, v170
	v_pk_mul_f32 v[56:57], v[56:57], v[158:159]
	v_pk_mul_f32 v[58:59], v[58:59], v[164:165]
	v_rcp_f32_e32 v179, v171
	v_rcp_f32_e32 v180, v172
	v_rcp_f32_e32 v181, v173
	v_pk_mul_f32 v[52:53], v[52:53], v[178:179]
	v_pk_mul_f32 v[54:55], v[54:55], v[180:181]
	v_pk_mul_f32 v[60:61], v[60:61], v[64:65]
	v_pk_mul_f32 v[62:63], v[62:63], v[66:67]
	v_pk_mul_f32 v[52:53], v[52:53], v[56:57]
	v_pk_mul_f32 v[54:55], v[54:55], v[58:59]
	v_cvt_pk_bf16_f32 v64, v60, v61
	v_cvt_pk_bf16_f32 v65, v62, v63
	v_cvt_pk_bf16_f32 v66, v52, v53
	v_cvt_pk_bf16_f32 v67, v54, v55
	global_store_dwordx4 v186, v[64:67], s[10:11]
	v_pk_mul_f32 v[48:49], v[48:49], v[210:211] op_sel_hi:[1,0]
	v_pk_mul_f32 v[50:51], v[50:51], v[210:211] op_sel_hi:[1,0]
	v_pk_mul_f32 v[40:41], v[40:41], v[210:211] op_sel_hi:[1,0]
	v_pk_mul_f32 v[42:43], v[42:43], v[210:211] op_sel_hi:[1,0]
	v_pk_mul_f32 v[44:45], v[44:45], v[210:211] op_sel_hi:[1,0]
	v_pk_mul_f32 v[46:47], v[46:47], v[210:211] op_sel_hi:[1,0]
	v_pk_mul_f32 v[36:37], v[36:37], v[210:211] op_sel_hi:[1,0]
	v_pk_mul_f32 v[38:39], v[38:39], v[210:211] op_sel_hi:[1,0]
	v_med3_f32 v158, v48, -4.0, 4.0
	v_med3_f32 v164, v50, -4.0, 4.0
	v_mul_f32_e32 v170, 0xbfb8aa3b, v44
	v_med3_f32 v159, v49, -4.0, 4.0
	v_med3_f32 v165, v51, -4.0, 4.0
	v_mul_f32_e32 v171, 0xbfb8aa3b, v45
	v_pk_mul_f32 v[160:161], v[158:159], v[158:159]
	v_pk_mul_f32 v[166:167], v[164:165], v[164:165]
	v_mul_f32_e32 v172, 0xbfb8aa3b, v46
	v_pk_fma_f32 v[160:161], v[160:161], s[72:73], -1.0 op_sel_hi:[1,0,0]
	v_pk_fma_f32 v[166:167], v[166:167], s[72:73], -1.0 op_sel_hi:[1,0,0]
	v_mul_f32_e32 v173, 0xbfb8aa3b, v47
	v_pk_fma_f32 v[162:163], v[160:161], s[74:75], v[198:199] op_sel_hi:[1,0,0]
	v_pk_fma_f32 v[168:169], v[166:167], s[74:75], v[198:199] op_sel_hi:[1,0,0]
	v_exp_f32_e32 v170, v170
	v_pk_fma_f32 v[162:163], v[160:161], v[162:163], s[2:3] op_sel_hi:[1,1,0]
	v_pk_fma_f32 v[168:169], v[166:167], v[168:169], s[2:3] op_sel_hi:[1,1,0]
	v_exp_f32_e32 v171, v171
	v_pk_fma_f32 v[162:163], v[160:161], v[162:163], s[28:29] op_sel_hi:[1,1,0]
	v_pk_fma_f32 v[168:169], v[166:167], v[168:169], s[28:29] op_sel_hi:[1,1,0]
	v_exp_f32_e32 v172, v172
	v_pk_fma_f32 v[162:163], v[160:161], v[162:163], s[30:31] op_sel_hi:[1,1,0]
	v_pk_fma_f32 v[168:169], v[166:167], v[168:169], s[30:31] op_sel_hi:[1,1,0]
	v_exp_f32_e32 v173, v173
	v_pk_fma_f32 v[162:163], v[160:161], v[162:163], s[48:49] op_sel_hi:[1,1,0]
	v_pk_fma_f32 v[168:169], v[166:167], v[168:169], s[48:49] op_sel_hi:[1,1,0]
	v_add_f32_e32 v170, 1.0, v170
	v_pk_fma_f32 v[162:163], v[160:161], v[162:163], s[50:51] op_sel_hi:[1,1,0]
	v_pk_fma_f32 v[168:169], v[166:167], v[168:169], s[50:51] op_sel_hi:[1,1,0]
	v_add_f32_e32 v171, 1.0, v171
	v_pk_fma_f32 v[162:163], v[160:161], v[162:163], s[52:53] op_sel_hi:[1,1,0]
	v_pk_fma_f32 v[168:169], v[166:167], v[168:169], s[52:53] op_sel_hi:[1,1,0]
	v_add_f32_e32 v172, 1.0, v172
	v_pk_fma_f32 v[160:161], v[160:161], v[162:163], s[54:55] op_sel_hi:[1,1,0]
	v_pk_fma_f32 v[166:167], v[166:167], v[168:169], s[54:55] op_sel_hi:[1,1,0]
	v_add_f32_e32 v173, 1.0, v173
	v_pk_fma_f32 v[158:159], v[158:159], v[160:161], 0.5 op_sel_hi:[1,1,0]
	v_pk_fma_f32 v[164:165], v[164:165], v[166:167], 0.5 op_sel_hi:[1,1,0]
	v_rcp_f32_e32 v178, v170
	v_pk_mul_f32 v[48:49], v[48:49], v[158:159]
	v_pk_mul_f32 v[50:51], v[50:51], v[164:165]
	v_rcp_f32_e32 v179, v171
	v_rcp_f32_e32 v180, v172
	v_rcp_f32_e32 v181, v173
	v_pk_mul_f32 v[44:45], v[44:45], v[178:179]
	v_pk_mul_f32 v[46:47], v[46:47], v[180:181]
	v_med3_f32 v158, v40, -4.0, 4.0
	v_med3_f32 v164, v42, -4.0, 4.0
	v_mul_f32_e32 v170, 0xbfb8aa3b, v36
	v_med3_f32 v159, v41, -4.0, 4.0
	v_med3_f32 v165, v43, -4.0, 4.0
	v_mul_f32_e32 v171, 0xbfb8aa3b, v37
	v_pk_mul_f32 v[160:161], v[158:159], v[158:159]
	v_pk_mul_f32 v[166:167], v[164:165], v[164:165]
	v_mul_f32_e32 v172, 0xbfb8aa3b, v38
	v_pk_fma_f32 v[160:161], v[160:161], s[72:73], -1.0 op_sel_hi:[1,0,0]
	v_pk_fma_f32 v[166:167], v[166:167], s[72:73], -1.0 op_sel_hi:[1,0,0]
	v_mul_f32_e32 v173, 0xbfb8aa3b, v39
	v_pk_fma_f32 v[162:163], v[160:161], s[74:75], v[198:199] op_sel_hi:[1,0,0]
	v_pk_fma_f32 v[168:169], v[166:167], s[74:75], v[198:199] op_sel_hi:[1,0,0]
	v_exp_f32_e32 v170, v170
	v_pk_fma_f32 v[162:163], v[160:161], v[162:163], s[2:3] op_sel_hi:[1,1,0]
	v_pk_fma_f32 v[168:169], v[166:167], v[168:169], s[2:3] op_sel_hi:[1,1,0]
	v_exp_f32_e32 v171, v171
	v_pk_fma_f32 v[162:163], v[160:161], v[162:163], s[28:29] op_sel_hi:[1,1,0]
	v_pk_fma_f32 v[168:169], v[166:167], v[168:169], s[28:29] op_sel_hi:[1,1,0]
	v_exp_f32_e32 v172, v172
	v_pk_fma_f32 v[162:163], v[160:161], v[162:163], s[30:31] op_sel_hi:[1,1,0]
	v_pk_fma_f32 v[168:169], v[166:167], v[168:169], s[30:31] op_sel_hi:[1,1,0]
	v_exp_f32_e32 v173, v173
	v_pk_fma_f32 v[162:163], v[160:161], v[162:163], s[48:49] op_sel_hi:[1,1,0]
	v_pk_fma_f32 v[168:169], v[166:167], v[168:169], s[48:49] op_sel_hi:[1,1,0]
	v_add_f32_e32 v170, 1.0, v170
	v_pk_fma_f32 v[162:163], v[160:161], v[162:163], s[50:51] op_sel_hi:[1,1,0]
	v_pk_fma_f32 v[168:169], v[166:167], v[168:169], s[50:51] op_sel_hi:[1,1,0]
	v_add_f32_e32 v171, 1.0, v171
	v_pk_fma_f32 v[162:163], v[160:161], v[162:163], s[52:53] op_sel_hi:[1,1,0]
	v_pk_fma_f32 v[168:169], v[166:167], v[168:169], s[52:53] op_sel_hi:[1,1,0]
	v_add_f32_e32 v172, 1.0, v172
	v_pk_fma_f32 v[160:161], v[160:161], v[162:163], s[54:55] op_sel_hi:[1,1,0]
	v_pk_fma_f32 v[166:167], v[166:167], v[168:169], s[54:55] op_sel_hi:[1,1,0]
	v_add_f32_e32 v173, 1.0, v173
	v_pk_fma_f32 v[158:159], v[158:159], v[160:161], 0.5 op_sel_hi:[1,1,0]
	v_pk_fma_f32 v[164:165], v[164:165], v[166:167], 0.5 op_sel_hi:[1,1,0]
	v_rcp_f32_e32 v178, v170
	v_pk_mul_f32 v[40:41], v[40:41], v[158:159]
	v_pk_mul_f32 v[42:43], v[42:43], v[164:165]
	v_rcp_f32_e32 v179, v171
	v_rcp_f32_e32 v180, v172
	v_rcp_f32_e32 v181, v173
	v_pk_mul_f32 v[36:37], v[36:37], v[178:179]
	v_pk_mul_f32 v[38:39], v[38:39], v[180:181]
	v_pk_mul_f32 v[44:45], v[44:45], v[48:49]
	v_pk_mul_f32 v[46:47], v[46:47], v[50:51]
	v_pk_mul_f32 v[36:37], v[36:37], v[40:41]
	v_pk_mul_f32 v[38:39], v[38:39], v[42:43]
	v_cvt_pk_bf16_f32 v48, v44, v45
	v_cvt_pk_bf16_f32 v49, v46, v47
	v_cvt_pk_bf16_f32 v50, v36, v37
	v_cvt_pk_bf16_f32 v51, v38, v39
	global_store_dwordx4 v187, v[48:51], s[10:11]
	v_pk_mul_f32 v[32:33], v[32:33], v[212:213] op_sel_hi:[1,0]
	v_pk_mul_f32 v[34:35], v[34:35], v[212:213] op_sel_hi:[1,0]
	v_pk_mul_f32 v[24:25], v[24:25], v[212:213] op_sel_hi:[1,0]
	v_pk_mul_f32 v[26:27], v[26:27], v[212:213] op_sel_hi:[1,0]
	v_pk_mul_f32 v[28:29], v[28:29], v[212:213] op_sel_hi:[1,0]
	v_pk_mul_f32 v[30:31], v[30:31], v[212:213] op_sel_hi:[1,0]
	v_pk_mul_f32 v[20:21], v[20:21], v[212:213] op_sel_hi:[1,0]
	v_pk_mul_f32 v[22:23], v[22:23], v[212:213] op_sel_hi:[1,0]
	v_med3_f32 v158, v32, -4.0, 4.0
	v_med3_f32 v164, v34, -4.0, 4.0
	v_mul_f32_e32 v170, 0xbfb8aa3b, v28
	v_med3_f32 v159, v33, -4.0, 4.0
	v_med3_f32 v165, v35, -4.0, 4.0
	v_mul_f32_e32 v171, 0xbfb8aa3b, v29
	v_pk_mul_f32 v[160:161], v[158:159], v[158:159]
	v_pk_mul_f32 v[166:167], v[164:165], v[164:165]
	v_mul_f32_e32 v172, 0xbfb8aa3b, v30
	v_pk_fma_f32 v[160:161], v[160:161], s[72:73], -1.0 op_sel_hi:[1,0,0]
	v_pk_fma_f32 v[166:167], v[166:167], s[72:73], -1.0 op_sel_hi:[1,0,0]
	v_mul_f32_e32 v173, 0xbfb8aa3b, v31
	v_pk_fma_f32 v[162:163], v[160:161], s[74:75], v[198:199] op_sel_hi:[1,0,0]
	v_pk_fma_f32 v[168:169], v[166:167], s[74:75], v[198:199] op_sel_hi:[1,0,0]
	v_exp_f32_e32 v170, v170
	v_pk_fma_f32 v[162:163], v[160:161], v[162:163], s[2:3] op_sel_hi:[1,1,0]
	v_pk_fma_f32 v[168:169], v[166:167], v[168:169], s[2:3] op_sel_hi:[1,1,0]
	v_exp_f32_e32 v171, v171
	v_pk_fma_f32 v[162:163], v[160:161], v[162:163], s[28:29] op_sel_hi:[1,1,0]
	v_pk_fma_f32 v[168:169], v[166:167], v[168:169], s[28:29] op_sel_hi:[1,1,0]
	v_exp_f32_e32 v172, v172
	v_pk_fma_f32 v[162:163], v[160:161], v[162:163], s[30:31] op_sel_hi:[1,1,0]
	v_pk_fma_f32 v[168:169], v[166:167], v[168:169], s[30:31] op_sel_hi:[1,1,0]
	v_exp_f32_e32 v173, v173
	v_pk_fma_f32 v[162:163], v[160:161], v[162:163], s[48:49] op_sel_hi:[1,1,0]
	v_pk_fma_f32 v[168:169], v[166:167], v[168:169], s[48:49] op_sel_hi:[1,1,0]
	v_add_f32_e32 v170, 1.0, v170
	v_pk_fma_f32 v[162:163], v[160:161], v[162:163], s[50:51] op_sel_hi:[1,1,0]
	v_pk_fma_f32 v[168:169], v[166:167], v[168:169], s[50:51] op_sel_hi:[1,1,0]
	v_add_f32_e32 v171, 1.0, v171
	v_pk_fma_f32 v[162:163], v[160:161], v[162:163], s[52:53] op_sel_hi:[1,1,0]
	v_pk_fma_f32 v[168:169], v[166:167], v[168:169], s[52:53] op_sel_hi:[1,1,0]
	v_add_f32_e32 v172, 1.0, v172
	v_pk_fma_f32 v[160:161], v[160:161], v[162:163], s[54:55] op_sel_hi:[1,1,0]
	v_pk_fma_f32 v[166:167], v[166:167], v[168:169], s[54:55] op_sel_hi:[1,1,0]
	v_add_f32_e32 v173, 1.0, v173
	v_pk_fma_f32 v[158:159], v[158:159], v[160:161], 0.5 op_sel_hi:[1,1,0]
	v_pk_fma_f32 v[164:165], v[164:165], v[166:167], 0.5 op_sel_hi:[1,1,0]
	v_rcp_f32_e32 v178, v170
	v_pk_mul_f32 v[32:33], v[32:33], v[158:159]
	v_pk_mul_f32 v[34:35], v[34:35], v[164:165]
	v_rcp_f32_e32 v179, v171
	v_rcp_f32_e32 v180, v172
	v_rcp_f32_e32 v181, v173
	v_pk_mul_f32 v[28:29], v[28:29], v[178:179]
	v_pk_mul_f32 v[30:31], v[30:31], v[180:181]
	v_med3_f32 v158, v24, -4.0, 4.0
	v_med3_f32 v164, v26, -4.0, 4.0
	v_mul_f32_e32 v170, 0xbfb8aa3b, v20
	v_med3_f32 v159, v25, -4.0, 4.0
	v_med3_f32 v165, v27, -4.0, 4.0
	v_mul_f32_e32 v171, 0xbfb8aa3b, v21
	v_pk_mul_f32 v[160:161], v[158:159], v[158:159]
	v_pk_mul_f32 v[166:167], v[164:165], v[164:165]
	v_mul_f32_e32 v172, 0xbfb8aa3b, v22
	v_pk_fma_f32 v[160:161], v[160:161], s[72:73], -1.0 op_sel_hi:[1,0,0]
	v_pk_fma_f32 v[166:167], v[166:167], s[72:73], -1.0 op_sel_hi:[1,0,0]
	v_mul_f32_e32 v173, 0xbfb8aa3b, v23
	v_pk_fma_f32 v[162:163], v[160:161], s[74:75], v[198:199] op_sel_hi:[1,0,0]
	v_pk_fma_f32 v[168:169], v[166:167], s[74:75], v[198:199] op_sel_hi:[1,0,0]
	v_exp_f32_e32 v170, v170
	v_pk_fma_f32 v[162:163], v[160:161], v[162:163], s[2:3] op_sel_hi:[1,1,0]
	v_pk_fma_f32 v[168:169], v[166:167], v[168:169], s[2:3] op_sel_hi:[1,1,0]
	v_exp_f32_e32 v171, v171
	v_pk_fma_f32 v[162:163], v[160:161], v[162:163], s[28:29] op_sel_hi:[1,1,0]
	v_pk_fma_f32 v[168:169], v[166:167], v[168:169], s[28:29] op_sel_hi:[1,1,0]
	v_exp_f32_e32 v172, v172
	v_pk_fma_f32 v[162:163], v[160:161], v[162:163], s[30:31] op_sel_hi:[1,1,0]
	v_pk_fma_f32 v[168:169], v[166:167], v[168:169], s[30:31] op_sel_hi:[1,1,0]
	v_exp_f32_e32 v173, v173
	v_pk_fma_f32 v[162:163], v[160:161], v[162:163], s[48:49] op_sel_hi:[1,1,0]
	v_pk_fma_f32 v[168:169], v[166:167], v[168:169], s[48:49] op_sel_hi:[1,1,0]
	v_add_f32_e32 v170, 1.0, v170
	v_pk_fma_f32 v[162:163], v[160:161], v[162:163], s[50:51] op_sel_hi:[1,1,0]
	v_pk_fma_f32 v[168:169], v[166:167], v[168:169], s[50:51] op_sel_hi:[1,1,0]
	v_add_f32_e32 v171, 1.0, v171
	v_pk_fma_f32 v[162:163], v[160:161], v[162:163], s[52:53] op_sel_hi:[1,1,0]
	v_pk_fma_f32 v[168:169], v[166:167], v[168:169], s[52:53] op_sel_hi:[1,1,0]
	v_add_f32_e32 v172, 1.0, v172
	v_pk_fma_f32 v[160:161], v[160:161], v[162:163], s[54:55] op_sel_hi:[1,1,0]
	v_pk_fma_f32 v[166:167], v[166:167], v[168:169], s[54:55] op_sel_hi:[1,1,0]
	v_add_f32_e32 v173, 1.0, v173
	v_pk_fma_f32 v[158:159], v[158:159], v[160:161], 0.5 op_sel_hi:[1,1,0]
	v_pk_fma_f32 v[164:165], v[164:165], v[166:167], 0.5 op_sel_hi:[1,1,0]
	v_rcp_f32_e32 v178, v170
	v_pk_mul_f32 v[24:25], v[24:25], v[158:159]
	v_pk_mul_f32 v[26:27], v[26:27], v[164:165]
	v_rcp_f32_e32 v179, v171
	v_rcp_f32_e32 v180, v172
	v_rcp_f32_e32 v181, v173
	v_pk_mul_f32 v[20:21], v[20:21], v[178:179]
	v_pk_mul_f32 v[22:23], v[22:23], v[180:181]
	v_pk_mul_f32 v[28:29], v[28:29], v[32:33]
	v_pk_mul_f32 v[30:31], v[30:31], v[34:35]
	v_pk_mul_f32 v[20:21], v[20:21], v[24:25]
	v_pk_mul_f32 v[22:23], v[22:23], v[26:27]
	v_cvt_pk_bf16_f32 v32, v28, v29
	v_cvt_pk_bf16_f32 v33, v30, v31
	v_cvt_pk_bf16_f32 v34, v20, v21
	v_cvt_pk_bf16_f32 v35, v22, v23
	global_store_dwordx4 v188, v[32:35], s[10:11]
	v_pk_mul_f32 v[16:17], v[16:17], v[214:215] op_sel_hi:[1,0]
	v_pk_mul_f32 v[18:19], v[18:19], v[214:215] op_sel_hi:[1,0]
	v_pk_mul_f32 v[8:9], v[8:9], v[214:215] op_sel_hi:[1,0]
	v_pk_mul_f32 v[10:11], v[10:11], v[214:215] op_sel_hi:[1,0]
	v_pk_mul_f32 v[12:13], v[12:13], v[214:215] op_sel_hi:[1,0]
	v_pk_mul_f32 v[14:15], v[14:15], v[214:215] op_sel_hi:[1,0]
	v_pk_mul_f32 v[4:5], v[4:5], v[214:215] op_sel_hi:[1,0]
	v_pk_mul_f32 v[6:7], v[6:7], v[214:215] op_sel_hi:[1,0]
	v_med3_f32 v158, v16, -4.0, 4.0
	v_med3_f32 v164, v18, -4.0, 4.0
	v_mul_f32_e32 v170, 0xbfb8aa3b, v12
	v_med3_f32 v159, v17, -4.0, 4.0
	v_med3_f32 v165, v19, -4.0, 4.0
	v_mul_f32_e32 v171, 0xbfb8aa3b, v13
	v_pk_mul_f32 v[160:161], v[158:159], v[158:159]
	v_pk_mul_f32 v[166:167], v[164:165], v[164:165]
	v_mul_f32_e32 v172, 0xbfb8aa3b, v14
	v_pk_fma_f32 v[160:161], v[160:161], s[72:73], -1.0 op_sel_hi:[1,0,0]
	v_pk_fma_f32 v[166:167], v[166:167], s[72:73], -1.0 op_sel_hi:[1,0,0]
	v_mul_f32_e32 v173, 0xbfb8aa3b, v15
	v_pk_fma_f32 v[162:163], v[160:161], s[74:75], v[198:199] op_sel_hi:[1,0,0]
	v_pk_fma_f32 v[168:169], v[166:167], s[74:75], v[198:199] op_sel_hi:[1,0,0]
	v_exp_f32_e32 v170, v170
	v_pk_fma_f32 v[162:163], v[160:161], v[162:163], s[2:3] op_sel_hi:[1,1,0]
	v_pk_fma_f32 v[168:169], v[166:167], v[168:169], s[2:3] op_sel_hi:[1,1,0]
	v_exp_f32_e32 v171, v171
	v_pk_fma_f32 v[162:163], v[160:161], v[162:163], s[28:29] op_sel_hi:[1,1,0]
	v_pk_fma_f32 v[168:169], v[166:167], v[168:169], s[28:29] op_sel_hi:[1,1,0]
	v_exp_f32_e32 v172, v172
	v_pk_fma_f32 v[162:163], v[160:161], v[162:163], s[30:31] op_sel_hi:[1,1,0]
	v_pk_fma_f32 v[168:169], v[166:167], v[168:169], s[30:31] op_sel_hi:[1,1,0]
	v_exp_f32_e32 v173, v173
	v_pk_fma_f32 v[162:163], v[160:161], v[162:163], s[48:49] op_sel_hi:[1,1,0]
	v_pk_fma_f32 v[168:169], v[166:167], v[168:169], s[48:49] op_sel_hi:[1,1,0]
	v_add_f32_e32 v170, 1.0, v170
	v_pk_fma_f32 v[162:163], v[160:161], v[162:163], s[50:51] op_sel_hi:[1,1,0]
	v_pk_fma_f32 v[168:169], v[166:167], v[168:169], s[50:51] op_sel_hi:[1,1,0]
	v_add_f32_e32 v171, 1.0, v171
	v_pk_fma_f32 v[162:163], v[160:161], v[162:163], s[52:53] op_sel_hi:[1,1,0]
	v_pk_fma_f32 v[168:169], v[166:167], v[168:169], s[52:53] op_sel_hi:[1,1,0]
	v_add_f32_e32 v172, 1.0, v172
	v_pk_fma_f32 v[160:161], v[160:161], v[162:163], s[54:55] op_sel_hi:[1,1,0]
	v_pk_fma_f32 v[166:167], v[166:167], v[168:169], s[54:55] op_sel_hi:[1,1,0]
	v_add_f32_e32 v173, 1.0, v173
	v_pk_fma_f32 v[158:159], v[158:159], v[160:161], 0.5 op_sel_hi:[1,1,0]
	v_pk_fma_f32 v[164:165], v[164:165], v[166:167], 0.5 op_sel_hi:[1,1,0]
	v_rcp_f32_e32 v178, v170
	v_pk_mul_f32 v[16:17], v[16:17], v[158:159]
	v_pk_mul_f32 v[18:19], v[18:19], v[164:165]
	v_rcp_f32_e32 v179, v171
	v_rcp_f32_e32 v180, v172
	v_rcp_f32_e32 v181, v173
	v_pk_mul_f32 v[12:13], v[12:13], v[178:179]
	v_pk_mul_f32 v[14:15], v[14:15], v[180:181]
	v_med3_f32 v158, v8, -4.0, 4.0
	v_med3_f32 v164, v10, -4.0, 4.0
	v_mul_f32_e32 v170, 0xbfb8aa3b, v4
	v_med3_f32 v159, v9, -4.0, 4.0
	v_med3_f32 v165, v11, -4.0, 4.0
	v_mul_f32_e32 v171, 0xbfb8aa3b, v5
	v_pk_mul_f32 v[160:161], v[158:159], v[158:159]
	v_pk_mul_f32 v[166:167], v[164:165], v[164:165]
	v_mul_f32_e32 v172, 0xbfb8aa3b, v6
	v_pk_fma_f32 v[160:161], v[160:161], s[72:73], -1.0 op_sel_hi:[1,0,0]
	v_pk_fma_f32 v[166:167], v[166:167], s[72:73], -1.0 op_sel_hi:[1,0,0]
	v_mul_f32_e32 v173, 0xbfb8aa3b, v7
	v_pk_fma_f32 v[162:163], v[160:161], s[74:75], v[198:199] op_sel_hi:[1,0,0]
	v_pk_fma_f32 v[168:169], v[166:167], s[74:75], v[198:199] op_sel_hi:[1,0,0]
	v_exp_f32_e32 v170, v170
	v_pk_fma_f32 v[162:163], v[160:161], v[162:163], s[2:3] op_sel_hi:[1,1,0]
	v_pk_fma_f32 v[168:169], v[166:167], v[168:169], s[2:3] op_sel_hi:[1,1,0]
	v_exp_f32_e32 v171, v171
	v_pk_fma_f32 v[162:163], v[160:161], v[162:163], s[28:29] op_sel_hi:[1,1,0]
	v_pk_fma_f32 v[168:169], v[166:167], v[168:169], s[28:29] op_sel_hi:[1,1,0]
	v_exp_f32_e32 v172, v172
	v_pk_fma_f32 v[162:163], v[160:161], v[162:163], s[30:31] op_sel_hi:[1,1,0]
	v_pk_fma_f32 v[168:169], v[166:167], v[168:169], s[30:31] op_sel_hi:[1,1,0]
	v_exp_f32_e32 v173, v173
	v_pk_fma_f32 v[162:163], v[160:161], v[162:163], s[48:49] op_sel_hi:[1,1,0]
	v_pk_fma_f32 v[168:169], v[166:167], v[168:169], s[48:49] op_sel_hi:[1,1,0]
	v_add_f32_e32 v170, 1.0, v170
	v_pk_fma_f32 v[162:163], v[160:161], v[162:163], s[50:51] op_sel_hi:[1,1,0]
	v_pk_fma_f32 v[168:169], v[166:167], v[168:169], s[50:51] op_sel_hi:[1,1,0]
	v_add_f32_e32 v171, 1.0, v171
	v_pk_fma_f32 v[162:163], v[160:161], v[162:163], s[52:53] op_sel_hi:[1,1,0]
	v_pk_fma_f32 v[168:169], v[166:167], v[168:169], s[52:53] op_sel_hi:[1,1,0]
	v_add_f32_e32 v172, 1.0, v172
	v_pk_fma_f32 v[160:161], v[160:161], v[162:163], s[54:55] op_sel_hi:[1,1,0]
	v_pk_fma_f32 v[166:167], v[166:167], v[168:169], s[54:55] op_sel_hi:[1,1,0]
	v_add_f32_e32 v173, 1.0, v173
	v_pk_fma_f32 v[158:159], v[158:159], v[160:161], 0.5 op_sel_hi:[1,1,0]
	v_pk_fma_f32 v[164:165], v[164:165], v[166:167], 0.5 op_sel_hi:[1,1,0]
	v_rcp_f32_e32 v178, v170
	v_pk_mul_f32 v[8:9], v[8:9], v[158:159]
	v_pk_mul_f32 v[10:11], v[10:11], v[164:165]
	v_rcp_f32_e32 v179, v171
	v_rcp_f32_e32 v180, v172
	v_rcp_f32_e32 v181, v173
	v_pk_mul_f32 v[4:5], v[4:5], v[178:179]
	v_pk_mul_f32 v[6:7], v[6:7], v[180:181]
	v_pk_mul_f32 v[12:13], v[12:13], v[16:17]
	v_pk_mul_f32 v[14:15], v[14:15], v[18:19]
	v_pk_mul_f32 v[4:5], v[4:5], v[8:9]
	v_pk_mul_f32 v[6:7], v[6:7], v[10:11]
	v_cvt_pk_bf16_f32 v16, v12, v13
	v_cvt_pk_bf16_f32 v17, v14, v15
	v_cvt_pk_bf16_f32 v18, v4, v5
	v_cvt_pk_bf16_f32 v19, v6, v7
	global_store_dwordx4 v189, v[16:19], s[10:11]
	s_andn2_b64 vcc, exec, s[6:7]
	s_mov_b64 s[0:1], -1
	s_cbranch_vccnz .LBB0_442
